# v38 stack + S5-A block GEMM B-fragment read pipelining + BTY set-up loop (both Toeplitz loads before one wait, kernarg s_load hoisted)
# speedup vs baseline: 1.0097x; 1.0010x over previous
.LBB0_1432:
	v_add_u32_e32 v2, -14, v30
	v_ashrrev_i32_e32 v3, 31, v2
	v_add_u32_e32 v6, -2, v30
	v_lshlrev_b64 v[2:3], 9, v[2:3]
	v_ashrrev_i32_e32 v7, 31, v6
	v_lshl_add_u64 v[2:3], v[26:27], 0, v[2:3]
	v_lshlrev_b64 v[6:7], 9, v[6:7]
	global_load_dwordx4 v[34:37], v[2:3], off
	v_lshl_add_u64 v[6:7], v[26:27], 0, v[6:7]
	global_load_dwordx4 v[6:9], v[6:7], off
	v_add_u32_e32 v2, -12, v30
	v_ashrrev_i32_e32 v3, 31, v2
	v_lshlrev_b64 v[2:3], 9, v[2:3]
	v_lshl_add_u64 v[2:3], v[26:27], 0, v[2:3]
	global_load_dwordx4 v[38:41], v[2:3], off
	v_ashrrev_i32_e32 v31, 31, v30
	v_lshlrev_b64 v[18:19], 9, v[30:31]
	v_lshl_add_u64 v[18:19], v[26:27], 0, v[18:19]
	global_load_dwordx4 v[18:21], v[18:19], off
	v_add_u32_e32 v2, -10, v30
	v_ashrrev_i32_e32 v3, 31, v2
	v_lshlrev_b64 v[2:3], 9, v[2:3]
	v_lshl_add_u64 v[2:3], v[26:27], 0, v[2:3]
	global_load_dwordx4 v[22:25], v[2:3], off
	v_add_u32_e32 v2, -8, v30
	v_ashrrev_i32_e32 v3, 31, v2
	v_lshlrev_b64 v[2:3], 9, v[2:3]
	v_lshl_add_u64 v[2:3], v[26:27], 0, v[2:3]
	global_load_dwordx4 v[10:13], v[2:3], off
	v_add_u32_e32 v2, -6, v30
	v_ashrrev_i32_e32 v3, 31, v2
	v_lshlrev_b64 v[2:3], 9, v[2:3]
	v_lshl_add_u64 v[2:3], v[26:27], 0, v[2:3]
	global_load_dwordx4 v[14:17], v[2:3], off
	ds_read_b128 v[108:111], v32
	ds_read_b128 v[112:115], v32 offset:8448
	ds_read_b128 v[116:119], v32 offset:16896
	ds_read_b128 v[120:123], v32 offset:25344
	ds_read_b128 v[124:127], v32 offset:64
	ds_read_b128 v[128:131], v32 offset:8512
	ds_read_b128 v[132:135], v32 offset:16960
	ds_read_b128 v[136:139], v32 offset:25408
	v_add_u32_e32 v2, -4, v30
	v_ashrrev_i32_e32 v3, 31, v2
	v_lshlrev_b64 v[2:3], 9, v[2:3]
	v_lshl_add_u64 v[2:3], v[26:27], 0, v[2:3]
	global_load_dwordx4 v[2:5], v[2:3], off
	s_mov_b32 s4, 0xffff4000
	s_add_i32 s13, s13, 8
	v_add_u32_e32 v30, 0x800, v30
	s_cmp_ge_i32 s13, s2
	s_waitcnt vmcnt(7)
	s_waitcnt lgkmcnt(7)
	v_mfma_f32_16x16x32_bf16 v[42:45], v[34:37], v[108:111], 0
	ds_read_b128 v[108:111], v32 offset:128
	s_waitcnt lgkmcnt(7)
	v_mfma_f32_16x16x32_bf16 v[46:49], v[34:37], v[112:115], 0
	ds_read_b128 v[112:115], v32 offset:8576
	s_waitcnt lgkmcnt(7)
	v_mfma_f32_16x16x32_bf16 v[50:53], v[34:37], v[116:119], 0
	ds_read_b128 v[116:119], v32 offset:17024
	s_waitcnt lgkmcnt(7)
	v_mfma_f32_16x16x32_bf16 v[34:37], v[34:37], v[120:123], 0
	ds_read_b128 v[120:123], v32 offset:25472
	s_waitcnt vmcnt(5)
	s_waitcnt lgkmcnt(7)
	v_mfma_f32_16x16x32_bf16 v[42:45], v[38:41], v[124:127], v[42:45]
	ds_read_b128 v[124:127], v32 offset:192
	s_waitcnt lgkmcnt(7)
	v_mfma_f32_16x16x32_bf16 v[46:49], v[38:41], v[128:131], v[46:49]
	ds_read_b128 v[128:131], v32 offset:8640
	s_waitcnt lgkmcnt(7)
	v_mfma_f32_16x16x32_bf16 v[50:53], v[38:41], v[132:135], v[50:53]
	ds_read_b128 v[132:135], v32 offset:17088
	s_waitcnt lgkmcnt(7)
	v_mfma_f32_16x16x32_bf16 v[34:37], v[38:41], v[136:139], v[34:37]
	ds_read_b128 v[136:139], v32 offset:25536
	s_waitcnt vmcnt(3)
	s_waitcnt lgkmcnt(7)
	v_mfma_f32_16x16x32_bf16 v[38:41], v[22:25], v[108:111], v[42:45]
	ds_read_b128 v[108:111], v32 offset:256
	s_nop 2
	s_waitcnt lgkmcnt(7)
	v_mfma_f32_16x16x32_bf16 v[42:45], v[22:25], v[112:115], v[46:49]
	ds_read_b128 v[112:115], v32 offset:8704
	s_nop 2
	s_waitcnt lgkmcnt(7)
	v_mfma_f32_16x16x32_bf16 v[46:49], v[22:25], v[116:119], v[50:53]
	ds_read_b128 v[116:119], v32 offset:17152
	s_nop 2
	s_waitcnt lgkmcnt(7)
	v_mfma_f32_16x16x32_bf16 v[22:25], v[22:25], v[120:123], v[34:37]
	ds_read_b128 v[120:123], v32 offset:25600
	s_nop 2
	s_waitcnt vmcnt(2)
	s_waitcnt lgkmcnt(7)
	v_mfma_f32_16x16x32_bf16 v[34:37], v[10:13], v[124:127], v[38:41]
	ds_read_b128 v[124:127], v32 offset:320
	s_nop 2
	s_waitcnt lgkmcnt(7)
	v_mfma_f32_16x16x32_bf16 v[38:41], v[10:13], v[128:131], v[42:45]
	ds_read_b128 v[128:131], v32 offset:8768
	s_nop 2
	s_waitcnt lgkmcnt(7)
	v_mfma_f32_16x16x32_bf16 v[42:45], v[10:13], v[132:135], v[46:49]
	ds_read_b128 v[132:135], v32 offset:17216
	s_nop 2
	s_waitcnt lgkmcnt(7)
	v_mfma_f32_16x16x32_bf16 v[10:13], v[10:13], v[136:139], v[22:25]
	ds_read_b128 v[136:139], v32 offset:25664
	s_nop 2
	s_waitcnt vmcnt(1)
	s_waitcnt lgkmcnt(7)
	v_mfma_f32_16x16x32_bf16 v[22:25], v[14:17], v[108:111], v[34:37]
	ds_read_b128 v[108:111], v32 offset:384
	s_nop 2
	s_waitcnt lgkmcnt(7)
	v_mfma_f32_16x16x32_bf16 v[34:37], v[14:17], v[112:115], v[38:41]
	ds_read_b128 v[112:115], v32 offset:8832
	s_nop 2
	s_waitcnt lgkmcnt(7)
	v_mfma_f32_16x16x32_bf16 v[38:41], v[14:17], v[116:119], v[42:45]
	ds_read_b128 v[116:119], v32 offset:17280
	s_nop 2
	s_waitcnt lgkmcnt(7)
	v_mfma_f32_16x16x32_bf16 v[10:13], v[14:17], v[120:123], v[10:13]
	ds_read_b128 v[120:123], v32 offset:25728
	s_waitcnt vmcnt(0)
	s_waitcnt lgkmcnt(7)
	v_mfma_f32_16x16x32_bf16 v[14:17], v[2:5], v[124:127], v[22:25]
	ds_read_b128 v[124:127], v32 offset:448
	s_nop 2
	s_waitcnt lgkmcnt(7)
	v_mfma_f32_16x16x32_bf16 v[22:25], v[2:5], v[128:131], v[34:37]
	ds_read_b128 v[128:131], v32 offset:8896
	s_nop 2
	s_waitcnt lgkmcnt(7)
	v_mfma_f32_16x16x32_bf16 v[34:37], v[2:5], v[132:135], v[38:41]
	ds_read_b128 v[132:135], v32 offset:17344
	s_nop 2
	s_waitcnt lgkmcnt(7)
	v_mfma_f32_16x16x32_bf16 v[2:5], v[2:5], v[136:139], v[10:13]
	ds_read_b128 v[136:139], v32 offset:25792
	s_nop 2
	s_waitcnt lgkmcnt(7)
	v_mfma_f32_16x16x32_bf16 v[10:13], v[6:9], v[108:111], v[14:17]
	s_nop 2
	s_waitcnt lgkmcnt(6)
	v_mfma_f32_16x16x32_bf16 v[22:25], v[6:9], v[112:115], v[22:25]
	s_waitcnt lgkmcnt(5)
	v_mfma_f32_16x16x32_bf16 v[34:37], v[6:9], v[116:119], v[34:37]
	s_waitcnt lgkmcnt(4)
	v_mfma_f32_16x16x32_bf16 v[2:5], v[6:9], v[120:123], v[2:5]
	s_waitcnt lgkmcnt(3)
	v_mfma_f32_16x16x32_bf16 v[14:17], v[18:21], v[124:127], v[10:13]
	s_waitcnt lgkmcnt(2)
	v_mfma_f32_16x16x32_bf16 v[10:13], v[18:21], v[128:131], v[22:25]
	s_nop 1
	s_waitcnt lgkmcnt(1)
	v_mfma_f32_16x16x32_bf16 v[6:9], v[18:21], v[132:135], v[34:37]
	s_waitcnt lgkmcnt(0)
	v_mfma_f32_16x16x32_bf16 v[2:5], v[18:21], v[136:139], v[2:5]
	v_add_co_u32_e32 v18, vcc, s4, v28
	s_movk_i32 s4, 0x8000
	s_nop 0
	v_addc_co_u32_e32 v19, vcc, -1, v29, vcc
	v_add_co_u32_e32 v20, vcc, s4, v28
	s_movk_i32 s4, 0xc000
	s_nop 0
	v_addc_co_u32_e32 v21, vcc, -1, v29, vcc
	global_store_dword v[18:19], v14, off offset:-192
	v_add_co_u32_e32 v14, vcc, s4, v28
	global_store_dword v[20:21], v15, off offset:-192
	s_nop 0
	v_addc_co_u32_e32 v15, vcc, -1, v29, vcc
	s_mov_b64 s[4:5], 0x200000
	global_store_dword v[14:15], v16, off offset:-192
	global_store_dword v[28:29], v17, off offset:-192
	global_store_dword v[18:19], v10, off offset:-128
	global_store_dword v[20:21], v11, off offset:-128
	global_store_dword v[14:15], v12, off offset:-128
	global_store_dword v[28:29], v13, off offset:-128
	global_store_dword v[18:19], v6, off offset:-64
	global_store_dword v[20:21], v7, off offset:-64
	global_store_dword v[14:15], v8, off offset:-64
	global_store_dword v[28:29], v9, off offset:-64
	global_store_dword v[18:19], v2, off
	global_store_dword v[20:21], v3, off
	global_store_dword v[14:15], v4, off
	global_store_dword v[28:29], v5, off
	v_lshl_add_u64 v[28:29], v[28:29], 0, s[4:5]
	s_cbranch_scc0 .LBB0_1432
